# adds: HGRN prep packs neighbouring channels by DPP and writes dwords (2 ds_write2_b32 instead of 8 ds_write_b16)
# speedup vs baseline: 1.0078x; 1.0078x over previous
; #define LAS __attribute__((address_space(3)))
; __device__ __forceinline__ int otid() { int t = threadIdx.x; asm volatile("" : "+v"(t)); return t; }
; template <bool DRY> __device__ __forceinline__ void hgrn_unit(LAS unsigned char* lds, int b, int h, int vs, int layer, bf16_t* Pm, const float* lbraw) {
;     using namespace hg;
;     const int tid = otid(), lane = tid & 63; const int wid = __builtin_amdgcn_readfirstlane(tid >> 6);
;     const size_t tok0 = (size_t)b * SEQ;
;     const int kl = lane & 15, tq = lane >> 4, kch = 16 * wid + kl;
;     (void)layer; (void)lbraw;
;     const bf16_t* qsrc = Pm + (tok0 + 4 * tq) * PW + PC_HQ + h * 128 + (kch & ~1);
;     const bf16_t* fsrc = Pm + (tok0 + 4 * tq) * PW + PC_HF + h * 128 + (kch & ~1);
;     const bool isv = tid < 128; const int vv = tid & 31, vtq = (tid >> 5) & 3;
;     const bf16_t* vsrc = Pm + (tok0 + 4 * vtq) * PW + PC_HI + h * 128 + vs * 32 + (vv & ~1);
;     constexpr int NSTEP = SEQ / 16;
;     for (int i = tid; i < SB / 4; i += NTHREADS) ((LAS unsigned*)(lds + OFF_S + SB))[i] = 0u;
;     Raw ra, rb;
;     load_raw(ra, qsrc, fsrc, vsrc, 0, isv);
;     prep(ra, lds, lane, kch, tq, isv, vv, vtq);
;     load_raw(ra, qsrc, fsrc, vsrc, 1, isv); load_raw(rb, qsrc, fsrc, vsrc, 2, isv);
;     f32x16 sacc = {};
;     const int c16 = lane & 15, kq = lane >> 4, r32 = lane & 31, hh = lane >> 5;
;     __syncthreads();
.LBB0_615:
	s_or_b64 exec, exec, s[6:7]
	s_ashr_i32 s6, s22, 4
	s_ashr_i32 s7, s6, 31
	v_bfe_u32 v9, v3, 4, 2
	s_lshl_b64 s[14:15], s[6:7], 11
	v_lshlrev_b32_e32 v8, 2, v9
	v_or_b32_e32 v0, s14, v8
	v_mov_b64_e32 v[4:5], s[4:5]
	v_bfe_u32 v12, v3, 5, 2
	s_ashr_i32 s28, s10, 6
	s_mov_b32 s65, s28
	v_mad_u64_u32 v[0:1], s[6:7], v0, s24, v[4:5]
	s_lshl_b32 s10, s22, 5
	v_lshl_or_b32 v6, v12, 2, s14
	s_and_b32 s6, s10, 0x180
	v_mad_u64_u32 v[4:5], s[8:9], v6, s24, v[4:5]
	v_and_b32_e32 v7, 15, v3
	s_lshl_b32 s34, s28, 4
	v_mad_i32_i24 v1, s15, v240, v1
	s_lshl_b32 s6, s6, 1
	s_mov_b32 s7, s29
	v_mad_i32_i24 v5, s15, v240, v5
	v_lshl_add_u64 v[0:1], v[0:1], 0, s[6:7]
	v_bitop3_b32 v10, s34, -2, v7 bitop3:0xc8
	v_lshl_add_u64 v[4:5], v[4:5], 0, s[6:7]
	s_and_b32 s7, s10, 0x60
	v_ashrrev_i32_e32 v11, 31, v10
	s_lshl_b32 s8, s7, 1
	s_mul_i32 s41, s14, 0x1d40
	s_add_u32 s38, s4, s41
	s_addc_u32 s39, s5, 0
	s_add_u32 s38, s38, s6
	s_addc_u32 s39, s39, 0
	s_add_u32 s38, s38, 0xd00
	s_addc_u32 s39, s39, 0
	s_mov_b32 s9, s29
	v_and_b32_e32 v6, 30, v3
	v_lshl_add_u64 v[0:1], v[10:11], 1, v[0:1]
	v_lshl_add_u64 v[4:5], v[4:5], 0, s[8:9]
	v_lshlrev_b32_e32 v10, 1, v6
	v_mov_b32_e32 v11, v2
	s_movk_i32 s7, 0x1000
	v_lshl_add_u64 v[4:5], v[4:5], 0, v[10:11]
	v_add_co_u32_e32 v10, vcc, s7, v0
	v_cmp_eq_u32_e64 s[50:51], 3, v9
	s_nop 0
	v_addc_co_u32_e32 v11, vcc, 0, v1, vcc
	v_add_co_u32_e32 v14, vcc, s7, v4
	s_movk_i32 s7, 0x2000
	s_nop 0
	v_addc_co_u32_e32 v15, vcc, 0, v5, vcc
	v_add_co_u32_e32 v16, vcc, s7, v0
	s_movk_i32 s7, 0x3000
	s_nop 0
	v_addc_co_u32_e32 v17, vcc, 0, v1, vcc
	v_add_co_u32_e32 v18, vcc, s7, v4
	s_movk_i32 s7, 0x4000
	s_nop 0
	v_addc_co_u32_e32 v19, vcc, 0, v5, vcc
	v_add_co_u32_e32 v20, vcc, s7, v0
	s_nop 1
	v_addc_co_u32_e32 v21, vcc, 0, v1, vcc
	s_nop 0
	s_nop 0
	s_nop 0
	s_nop 0
	v_add_co_u32_e32 v10, vcc, s7, v4
	s_movk_i32 s7, 0x6000
	s_nop 0
	v_addc_co_u32_e32 v11, vcc, 0, v5, vcc
	v_add_co_u32_e32 v10, vcc, s7, v0
	s_nop 1
	v_addc_co_u32_e32 v11, vcc, 0, v1, vcc
	v_add_co_u32_e32 v18, vcc, s7, v4
	s_movk_i32 s7, 0x440
	s_nop 0
	v_addc_co_u32_e32 v19, vcc, 0, v5, vcc
	s_nop 0
	v_and_b32_e32 v19, 1, v3
	v_cmp_eq_u32_e64 s[44:45], 0, v19
	v_and_b32_e32 v11, 63, v3
	v_cmp_gt_u32_e64 s[46:47], 16, v11
	v_cmp_lt_u32_e64 s[48:49], 31, v11
	v_or_b32_e32 v10, s34, v7
	v_lshl_add_u32 v36, v10, 1, 0
	v_mad_u32_u24 v42, v9, s7, v36
	v_bfe_u32 v140, v234, 4, 2
	v_mul_u32_u24_e32 v136, 0x440, v140
	v_lshrrev_b32_e32 v140, 6, v234
	v_and_b32_e32 v141, 15, v234
	v_lshl_or_b32 v140, v140, 4, v141
	v_lshrrev_b32_e32 v140, 1, v140
	v_lshl_add_u32 v136, v140, 2, v136
	v_add_u32_e32 v136, 0xd400, v136
	v_bfe_i32 v145, v234, 4, 1
	v_and_b32_e32 v151, 1, v234
	v_mov_b32_e32 v152, 0x2020000
	v_mul_lo_u32 v151, v151, v152
	v_add_u32_e32 v151, 0x1000c0c, v151
	v_and_b32_e32 v186, 1, v234
	v_mov_b32_e32 v187, 0x403fbfc
	v_mul_lo_u32 v154, v186, v187
	v_add_u32_e32 v154, 0x1000504, v154
	v_add_u32_e32 v155, 0x2020202, v154
	v_mul_u32_u24_e32 v187, 0x220, v186
	v_add_u32_e32 v186, 0x3800, v187
	v_and_b32_e32 v144, 1, v234
	v_lshl_add_u32 v144, v144, 1, v136
	v_bfe_u32 v140, v234, 5, 2
	v_and_b32_e32 v141, 31, v234
	v_lshrrev_b32_e32 v141, 1, v141
	v_lshlrev_b32_e32 v141, 2, v141
	v_lshl_add_u32 v137, v140, 8, v141
	v_add_u32_e32 v137, 0xf600, v137
	v_and_b32_e32 v140, 63, v234
	v_lshrrev_b32_e32 v141, 4, v140
	v_lshrrev_b32_e32 v142, 6, v234
	v_and_b32_e32 v143, 3, v142
	v_lshl_add_u32 v141, v143, 2, v141
	v_mul_u32_u24_e32 v138, 0x1d40, v141
	v_and_b32_e32 v141, 15, v140
	v_lshl_add_u32 v138, v141, 4, v138
	v_lshrrev_b32_e32 v142, 2, v142
	v_lshl_add_u32 v138, v142, 10, v138
	v_lshrrev_b32_e32 v141, 2, v140
	v_mul_u32_u24_e32 v139, 0x1d40, v141
	v_and_b32_e32 v141, 3, v140
	v_lshl_add_u32 v139, v141, 4, v139
	v_add_u32_e32 v139, 0x800, v139
	v_add_u32_e32 v139, s8, v139
	s_mul_i32 s64, s65, 0x440
	s_add_i32 s64, s64, 0xd400
	s_mov_b64 s[42:43], s[38:39]
	s_cmp_lg_u32 s65, 7
	s_cbranch_scc1 .Lhg_pro_nov
	s_add_i32 m0, s64, 0
	s_nop 0
	global_load_lds_dwordx4 v138, s[42:43]
	s_mov_b32 m0, 0xf600
	s_nop 0
	global_load_lds_dwordx4 v139, s[42:43]
	s_add_u32 s42, s42, 0x1d400
	s_addc_u32 s43, s43, 0
	s_add_i32 m0, s64, 9792
	s_nop 0
	global_load_lds_dwordx4 v138, s[42:43]
	s_mov_b32 m0, 0x11c40
	s_nop 0
	global_load_lds_dwordx4 v139, s[42:43]
	s_add_u32 s42, s42, 0x1d400
	s_addc_u32 s43, s43, 0
	s_add_i32 m0, s64, 19584
	s_nop 0
	global_load_lds_dwordx4 v138, s[42:43]
	s_mov_b32 m0, 0x14280
	s_nop 0
	global_load_lds_dwordx4 v139, s[42:43]
	s_add_u32 s42, s42, 0x1d400
	s_addc_u32 s43, s43, 0
	s_add_i32 m0, s64, 29376
	s_nop 0
	global_load_lds_dwordx4 v138, s[42:43]
	s_mov_b32 m0, 0x168c0
	s_nop 0
	global_load_lds_dwordx4 v139, s[42:43]
	s_waitcnt vmcnt(4)
	s_branch .Lhg_pro_done

; #define LAS __attribute__((address_space(3)))
; __device__ __forceinline__ unsigned cvtpk(float lo, float hi) { f32x2_t v = {lo, hi}; bf16x2_t b = __builtin_convertvector(v, bf16x2_t); return __builtin_bit_cast(unsigned, b); }
; __device__ __forceinline__ void prep(const Raw& Rin, LAS unsigned char* buf, int lane, int kch, int tq, bool isv, int vv, int vtq) {
;     Raw R = Rin; const bool kodd = kch & 1, vodd = vv & 1;
; #pragma unroll
;     for (int i = 0; i < 4; ++i) { asm volatile("" : "+v"(R.q[i])); asm volatile("" : "+v"(R.f[i])); asm volatile("" : "+v"(R.v[i])); }
;     float qv[4], kk[4], c[4]; float run = 0.f;
; #pragma unroll
;     for (int i = 0; i < 4; ++i) {
;         qv[i] = __uint_as_float(kodd ? (R.q[i] & 0xffff0000u) : (R.q[i] << 16));
;         const float l2 = __uint_as_float(kodd ? (R.f[i] & 0xffff0000u) : (R.f[i] << 16));
;         kk[i] = 1.f - __builtin_amdgcn_exp2f(l2);
;         run += l2; c[i] = run;
;     }
;     const float p1 = __shfl(run, (lane - 16) & 63), p2 = __shfl(run, (lane - 32) & 63), p3 = __shfl(run, (lane - 48) & 63);
;     const float off = (tq >= 1 ? p1 : 0.f) + (tq >= 2 ? p2 : 0.f) + (tq >= 3 ? p3 : 0.f);
;     const float btot = __shfl(off + run, 48 + (lane & 15));
;     unsigned short kf[4];
; #pragma unroll
;     for (int i = 0; i < 4; ++i) {
;         const float bt = off + c[i];
;         const float qf = qv[i] * __builtin_amdgcn_exp2f(bt), kfv = kk[i] * __builtin_amdgcn_exp2f(-bt);
;         const unsigned pk = cvtpk(qf, kfv);
;         *(LAS unsigned short*)(buf + OFF_QF + (4 * tq + i) * STR + kch * 2) = (unsigned short)(pk & 0xffffu);
;         kf[i] = (unsigned short)(pk >> 16);
;         *(LAS unsigned short*)(buf + OFF_KF + (4 * tq + i) * STR + kch * 2) = kf[i];
;     }
;     *(LAS u32x2*)(buf + OFF_KFT + kch * 32 + tq * 8) = (u32x2){(unsigned)kf[0] | ((unsigned)kf[1] << 16), (unsigned)kf[2] | ((unsigned)kf[3] << 16)};
;     if (tq == 0) *(LAS float*)(buf + OFF_D + kch * 4) = __builtin_amdgcn_exp2f(btot);
;     if (isv) { unsigned v0 = vodd ? R.v[0] >> 16 : R.v[0] & 0xffffu, v1 = vodd ? R.v[1] >> 16 : R.v[1] & 0xffffu, v2 = vodd ? R.v[2] >> 16 : R.v[2] & 0xffffu, v3 = vodd ? R.v[3] >> 16 : R.v[3] & 0xffffu;
;         *(LAS u32x2*)(buf + OFF_VT + vv * 32 + vtq * 8) = (u32x2){v0 | (v1 << 16), v2 | (v3 << 16)}; }
; }
.Lhg_nov_a:
	s_add_i32 s41, s7, 1
	s_and_b32 s41, s41, 3
	s_mul_i32 s41, s41, 9792
	v_add_u32_e32 v140, s41, v136
	v_add_u32_e32 v141, s41, v137
	v_add_u32_e32 v153, 0x1100, v140
	ds_read2_b32 v[156:157], v153 offset1:64
	ds_read2_b32 v[158:159], v153 offset0:128 offset1:192
	ds_read2_b32 v[160:161], v140 offset1:64
	ds_read2_b32 v[162:163], v140 offset0:128 offset1:192
	ds_read2_b32 v[40:41], v141 offset1:16
	ds_read2_b32 v[164:165], v141 offset0:32 offset1:48
	s_waitcnt lgkmcnt(4)
	v_perm_b32 v0, v156, v156, v151
	v_perm_b32 v1, v157, v157, v151
	v_perm_b32 v3, v158, v158, v151
	v_perm_b32 v56, v159, v159, v151
	v_exp_f32_e32 v81, v0
	v_exp_f32_e32 v83, v1
	v_exp_f32_e32 v87, v3
	v_exp_f32_e32 v54, v56
	v_add_f32_e32 v1, v0, v1
	v_add_f32_e32 v3, v1, v3
	v_add_f32_e32 v63, v3, v56
	v_mov_b32_e32 v146, v63
	v_mov_b32_e32 v147, v63
	v_sub_f32_e32 v81, 1.0, v81
	v_sub_f32_e32 v83, 1.0, v83
	v_permlane16_swap_b32_e32 v146, v147
	v_sub_f32_e32 v87, 1.0, v87
	v_add_f32_e32 v148, v146, v147
	v_mov_b32_e32 v149, v148
	v_and_b32_e32 v150, v146, v145
	s_nop 0
	v_permlane32_swap_b32_e32 v148, v149
	v_cndmask_b32_e64 v52, 0, v148, s[48:49]
	v_add_f32_e32 v52, v52, v150
	s_waitcnt lgkmcnt(0)
	v_perm_b32 v78, v160, v160, v151
	v_perm_b32 v62, v161, v161, v151
	v_perm_b32 v84, v162, v162, v151
	v_perm_b32 v88, v163, v163, v151
	v_add_f32_e32 v0, v0, v52
	v_exp_f32_e32 v80, v0
	v_exp_f32_e64 v79, -v0
	v_add_f32_e32 v1, v1, v52
	v_sub_f32_e32 v91, 1.0, v54
	v_add_f32_e32 v54, v63, v52
	v_exp_f32_e32 v82, v1
	v_exp_f32_e64 v63, -v1
	v_add_f32_e32 v3, v3, v52
	v_pk_mul_f32 v[78:79], v[80:81], v[78:79]
	v_exp_f32_e32 v86, v3
	v_exp_f32_e64 v85, -v3
	v_cvt_pk_bf16_f32 v170, v78, v79
	v_exp_f32_e32 v90, v54
	v_exp_f32_e64 v89, -v54
	v_add_u32_e32 v184, v26, v43
	v_pk_mul_f32 v[62:63], v[82:83], v[62:63]
	v_add_f32_e32 v0, v148, v149
	v_cvt_pk_bf16_f32 v171, v62, v63
	v_pk_mul_f32 v[62:63], v[86:87], v[84:85]
	v_and_b32_e32 v184, -4, v184
	v_cvt_pk_bf16_f32 v172, v62, v63
	v_pk_mul_f32 v[78:79], v[90:91], v[88:89]
	v_add_u32_e32 v184, v184, v186
	v_cvt_pk_bf16_f32 v173, v78, v79
	v_perm_b32 v62, v171, v170, s17
	v_perm_b32 v63, v173, v172, s17
	v_cndmask_b32_e64 v174, v170, v172, s[44:45]
	v_cndmask_b32_e64 v175, v171, v173, s[44:45]
	v_cndmask_b32_e64 v176, v172, v170, s[44:45]
	v_cndmask_b32_e64 v177, v173, v171, s[44:45]
	v_add_u32_e32 v185, 0x1100, v184
	v_mov_b32_dpp v178, v174 quad_perm:[1,0,3,2] row_mask:0xf bank_mask:0xf
	v_mov_b32_dpp v179, v175 quad_perm:[1,0,3,2] row_mask:0xf bank_mask:0xf
	v_add_u32_e32 v1, v27, v37
	v_perm_b32 v180, v176, v178, v154
	v_perm_b32 v181, v177, v179, v154
	v_perm_b32 v182, v176, v178, v155
	v_perm_b32 v183, v177, v179, v155
	ds_write2_b32 v184, v180, v181 offset1:68
	ds_write2_b32 v185, v182, v183 offset1:68
	ds_write_b64 v1, v[62:63] offset:23040
	s_and_saveexec_b64 s[14:15], s[46:47]
	s_cbranch_execz .LBB0_627
	s_waitcnt lgkmcnt(9)
	v_exp_f32_e32 v0, v0
	v_add_u32_e32 v1, v27, v45
	ds_write_b32 v1, v0 offset:28160

; #define LAS __attribute__((address_space(3)))
; __device__ __forceinline__ unsigned cvtpk(float lo, float hi) { f32x2_t v = {lo, hi}; bf16x2_t b = __builtin_convertvector(v, bf16x2_t); return __builtin_bit_cast(unsigned, b); }
; __device__ __forceinline__ void prep(const Raw& Rin, LAS unsigned char* buf, int lane, int kch, int tq, bool isv, int vv, int vtq) {
;     Raw R = Rin; const bool kodd = kch & 1, vodd = vv & 1;
; #pragma unroll
;     for (int i = 0; i < 4; ++i) { asm volatile("" : "+v"(R.q[i])); asm volatile("" : "+v"(R.f[i])); asm volatile("" : "+v"(R.v[i])); }
;     float qv[4], kk[4], c[4]; float run = 0.f;
; #pragma unroll
;     for (int i = 0; i < 4; ++i) {
;         qv[i] = __uint_as_float(kodd ? (R.q[i] & 0xffff0000u) : (R.q[i] << 16));
;         const float l2 = __uint_as_float(kodd ? (R.f[i] & 0xffff0000u) : (R.f[i] << 16));
;         kk[i] = 1.f - __builtin_amdgcn_exp2f(l2);
;         run += l2; c[i] = run;
;     }
;     const float p1 = __shfl(run, (lane - 16) & 63), p2 = __shfl(run, (lane - 32) & 63), p3 = __shfl(run, (lane - 48) & 63);
;     const float off = (tq >= 1 ? p1 : 0.f) + (tq >= 2 ? p2 : 0.f) + (tq >= 3 ? p3 : 0.f);
;     const float btot = __shfl(off + run, 48 + (lane & 15));
;     unsigned short kf[4];
; #pragma unroll
;     for (int i = 0; i < 4; ++i) {
;         const float bt = off + c[i];
;         const float qf = qv[i] * __builtin_amdgcn_exp2f(bt), kfv = kk[i] * __builtin_amdgcn_exp2f(-bt);
;         const unsigned pk = cvtpk(qf, kfv);
;         *(LAS unsigned short*)(buf + OFF_QF + (4 * tq + i) * STR + kch * 2) = (unsigned short)(pk & 0xffffu);
;         kf[i] = (unsigned short)(pk >> 16);
;         *(LAS unsigned short*)(buf + OFF_KF + (4 * tq + i) * STR + kch * 2) = kf[i];
;     }
;     *(LAS u32x2*)(buf + OFF_KFT + kch * 32 + tq * 8) = (u32x2){(unsigned)kf[0] | ((unsigned)kf[1] << 16), (unsigned)kf[2] | ((unsigned)kf[3] << 16)};
;     if (tq == 0) *(LAS float*)(buf + OFF_D + kch * 4) = __builtin_amdgcn_exp2f(btot);
;     if (isv) { unsigned v0 = vodd ? R.v[0] >> 16 : R.v[0] & 0xffffu, v1 = vodd ? R.v[1] >> 16 : R.v[1] & 0xffffu, v2 = vodd ? R.v[2] >> 16 : R.v[2] & 0xffffu, v3 = vodd ? R.v[3] >> 16 : R.v[3] & 0xffffu;
;         *(LAS u32x2*)(buf + OFF_VT + vv * 32 + vtq * 8) = (u32x2){v0 | (v1 << 16), v2 | (v3 << 16)}; }
; }
.Lhg_nov_b:
	s_add_i32 s41, s7, 2
	s_and_b32 s41, s41, 3
	s_mul_i32 s41, s41, 9792
	v_add_u32_e32 v140, s41, v136
	v_add_u32_e32 v141, s41, v137
	v_add_u32_e32 v153, 0x1100, v140
	ds_read2_b32 v[156:157], v153 offset1:64
	ds_read2_b32 v[158:159], v153 offset0:128 offset1:192
	ds_read2_b32 v[160:161], v140 offset1:64
	ds_read2_b32 v[162:163], v140 offset0:128 offset1:192
	ds_read2_b32 v[166:167], v141 offset1:16
	ds_read2_b32 v[168:169], v141 offset0:32 offset1:48
	s_waitcnt lgkmcnt(4)
	v_perm_b32 v0, v156, v156, v151
	v_perm_b32 v1, v157, v157, v151
	v_perm_b32 v3, v158, v158, v151
	v_perm_b32 v72, v159, v159, v151
	v_exp_f32_e32 v81, v0
	v_exp_f32_e32 v85, v1
	v_exp_f32_e32 v87, v3
	v_exp_f32_e32 v68, v72
	v_add_f32_e32 v1, v0, v1
	v_add_f32_e32 v3, v1, v3
	v_add_f32_e32 v75, v3, v72
	v_mov_b32_e32 v146, v75
	v_mov_b32_e32 v147, v75
	v_sub_f32_e32 v81, 1.0, v81
	v_sub_f32_e32 v85, 1.0, v85
	v_permlane16_swap_b32_e32 v146, v147
	v_sub_f32_e32 v87, 1.0, v87
	v_add_f32_e32 v148, v146, v147
	v_mov_b32_e32 v149, v148
	v_and_b32_e32 v150, v146, v145
	s_nop 0
	v_permlane32_swap_b32_e32 v148, v149
	v_cndmask_b32_e64 v72, 0, v148, s[48:49]
	v_add_f32_e32 v72, v72, v150
	s_waitcnt lgkmcnt(0)
	v_perm_b32 v66, v160, v160, v151
	v_perm_b32 v82, v161, v161, v151
	v_perm_b32 v74, v162, v162, v151
	v_perm_b32 v76, v163, v163, v151
	v_add_f32_e32 v0, v0, v72
	v_exp_f32_e32 v80, v0
	v_exp_f32_e64 v67, -v0
	v_add_f32_e32 v1, v1, v72
	v_exp_f32_e32 v84, v1
	v_exp_f32_e64 v83, -v1
	v_sub_f32_e32 v89, 1.0, v68
	v_add_f32_e32 v68, v75, v72
	v_add_f32_e32 v3, v3, v72
	v_pk_mul_f32 v[66:67], v[80:81], v[66:67]
	v_exp_f32_e32 v86, v3
	v_exp_f32_e64 v75, -v3
	v_exp_f32_e32 v88, v68
	v_exp_f32_e64 v77, -v68
	v_cvt_pk_bf16_f32 v170, v66, v67
	v_add_f32_e32 v0, v148, v149
	v_add_u32_e32 v184, v36, v43
	v_pk_mul_f32 v[66:67], v[84:85], v[82:83]
	v_and_b32_e32 v184, -4, v184
	v_cvt_pk_bf16_f32 v171, v66, v67
	v_pk_mul_f32 v[66:67], v[86:87], v[74:75]
	v_pk_mul_f32 v[74:75], v[88:89], v[76:77]
	v_add_u32_e32 v184, v184, v187
	v_cvt_pk_bf16_f32 v172, v66, v67
	v_cvt_pk_bf16_f32 v173, v74, v75
	v_perm_b32 v66, v171, v170, s17
	v_perm_b32 v67, v173, v172, s17
	v_cndmask_b32_e64 v174, v170, v172, s[44:45]
	v_cndmask_b32_e64 v175, v171, v173, s[44:45]
	v_cndmask_b32_e64 v176, v172, v170, s[44:45]
	v_cndmask_b32_e64 v177, v173, v171, s[44:45]
	v_add_u32_e32 v185, 0x1100, v184
	v_mov_b32_dpp v178, v174 quad_perm:[1,0,3,2] row_mask:0xf bank_mask:0xf
	v_mov_b32_dpp v179, v175 quad_perm:[1,0,3,2] row_mask:0xf bank_mask:0xf
	v_perm_b32 v180, v176, v178, v154
	v_perm_b32 v181, v177, v179, v154
	v_perm_b32 v182, v176, v178, v155
	v_perm_b32 v183, v177, v179, v155
	ds_write2_b32 v184, v180, v181 offset1:68
	ds_write2_b32 v185, v182, v183 offset1:68
	ds_write_b64 v38, v[66:67] offset:8704
	s_and_saveexec_b64 s[14:15], s[46:47]
	s_cbranch_execz .LBB0_638
	s_waitcnt lgkmcnt(9)
	v_exp_f32_e32 v0, v0
	v_add_u32_e32 v1, v27, v45
	ds_write_b32 v1, v0 offset:13824
